# w_out-type GEMM epilogue: f32 residual rows prefetched one batch ahead into spare registers (4 serialized load round trips overlapped with the previous batch's math and stores)
# baseline (speedup 1.0000x reference)
; #define PG8_LAS __attribute__((address_space(3)))
;     __device__ __forceinline__ void core(const f32x4 (&acc)[2][2][4][2], const Unit& u, int wr, int wc, int fr, int fq, const float (&rsc)[2][4]) const {
;     ...
;             u32x4 va[MB][2]; u32x2 vb[MB][2];
;             f32x4 xa[MB][2], xb[MB][2];
; #pragma unroll
;             for (int m = 0; m < MB; ++m)
; #pragma unroll
;                 for (int bj = 0; bj < 2; ++bj) { const size_t idx = (size_t)(row0 + ai * HALF + (mh + m) * 16) * D + col0 + bj * HALF;
;                     if (F32IN) { xa[m][bj] = *(const f32x4*)(Xin + idx); xb[m][bj] = *(const f32x4*)(Xin + idx + 4); }
;                     else { va[m][bj] = *(const u32x4*)(Hb + idx); vb[m][bj] = *(const u32x2*)(Hl + idx); } }
;     __device__ __forceinline__ void gs(const f32x4 (&acc)[2][2][4][2], const Unit& u, int wr, int wc, int fr, int fq, const PG8_LAS float* rtab) const {
;         float rsc[2][4];
; #pragma unroll
;         for (int ai = 0; ai < 2; ++ai)
; #pragma unroll
;             for (int m = 0; m < 4; ++m) rsc[ai][m] = rtab[3 * 256 + ai * HALF + wr * 64 + m * 16 + fr];
.LBB0_1040:
	v_lshl_add_u32 v164, s12, 8, v183
	v_lshl_or_b32 v162, s56, 8, v189
	v_ashrrev_i32_e32 v163, 31, v162
	v_ashrrev_i32_e32 v165, 31, v164
	v_lshl_add_u64 v[166:167], v[162:163], 2, s[28:29]
	v_lshlrev_b64 v[2:3], 13, v[164:165]
	v_lshl_add_u64 v[132:133], v[166:167], 0, v[2:3]
	global_load_dwordx4 v[184:187], v[132:133], off
	global_load_dwordx4 v[192:195], v[132:133], off offset:16
	global_load_dwordx4 v[196:199], v[132:133], off offset:512
	s_add_i32 s18, s18, s65
	v_lshl_add_u32 v0, v178, 2, s18
	v_add_u32_e32 v0, 0xc00, v0
	ds_read2_b32 v[174:175], v0 offset1:16
	ds_read2_b32 v[170:171], v0 offset0:32 offset1:48
	ds_read2_b32 v[168:169], v0 offset0:128 offset1:144
	ds_read2_b32 v[2:3], v0 offset0:160 offset1:176
	global_load_dwordx4 v[200:203], v[132:133], off offset:528
	v_or_b32_e32 v172, 16, v164
	v_ashrrev_i32_e32 v173, 31, v172
	v_lshlrev_b64 v[136:137], 13, v[172:173]
	v_lshlrev_b64 v[134:135], 11, v[164:165]
	v_lshl_add_u64 v[136:137], v[166:167], 0, v[136:137]
	v_lshl_add_u64 v[204:205], v[134:135], 0, v[162:163]
	global_load_dwordx4 v[140:143], v[136:137], off offset:16
	global_load_dwordx4 v[144:147], v[136:137], off
	global_load_dwordx4 v[132:135], v[136:137], off offset:528
	s_nop 0
	global_load_dwordx4 v[136:139], v[136:137], off offset:512
	v_or_b32_e32 v252, 32, v164
	v_ashrrev_i32_e32 v253, 31, v252
	v_lshlrev_b64 v[252:253], 13, v[252:253]
	v_lshl_add_u64 v[252:253], v[166:167], 0, v[252:253]
	global_load_dwordx4 v[214:217], v[252:253], off offset:16
	global_load_dwordx4 v[218:221], v[252:253], off
	global_load_dwordx4 v[236:239], v[252:253], off offset:528
	global_load_dwordx4 v[240:243], v[252:253], off offset:512
	v_or_b32_e32 v252, 48, v164
	v_ashrrev_i32_e32 v253, 31, v252
	v_lshlrev_b64 v[252:253], 13, v[252:253]
	v_lshl_add_u64 v[252:253], v[166:167], 0, v[252:253]
	global_load_dwordx4 v[244:247], v[252:253], off offset:16
	global_load_dwordx4 v[248:251], v[252:253], off
	global_load_dwordx4 v[148:151], v[252:253], off offset:528
	global_load_dwordx4 v[152:155], v[252:253], off offset:512
	v_lshl_add_u64 v[206:207], v[204:205], 1, s[42:43]
	v_mov_b32_e32 v180, v1
	v_mov_b32_e32 v181, v1
	v_lshl_add_u64 v[208:209], s[44:45], 0, v[204:205]
	v_or_b32_e32 v204, 0x80, v204
	s_waitcnt vmcnt(8) lgkmcnt(0)
; __device__ __forceinline__ unsigned cvt_pk_bf16(float lo, float hi) { unsigned r; asm volatile("v_cvt_pk_bf16_f32 %0, %1, %2" : "=v"(r) : "v"(lo), "v"(hi)); return r; }
;     __device__ __forceinline__ void core(const f32x4 (&acc)[2][2][4][2], const Unit& u, int wr, int wc, int fr, int fq, const float (&rsc)[2][4]) const {
;     ...
;             for (int m = 0; m < MB; ++m) { const int row = row0 + ai * HALF + (mh + m) * 16; float sq = 0.f;
;                 const float rs1 = rsc[ai][mh + m];
; #pragma unroll
;                 for (int bj = 0; bj < 2; ++bj) { const size_t idx = (size_t)row * D + col0 + bj * HALF;
;                     unsigned hw[4]; int lw[2] = {0, 0};
; #pragma unroll
;                     for (int pq = 0; pq < 4; ++pq) {
;                         float h0, h1;
;                         if (F32IN) { h0 = (pq < 2) ? xa[m][bj][2 * pq] : xb[m][bj][2 * pq - 4]; h1 = (pq < 2) ? xa[m][bj][2 * pq + 1] : xb[m][bj][2 * pq - 3]; }
;                         else { const unsigned a = va[m][bj][pq]; const int bw = (int)vb[m][bj][pq >> 1]; const hf32x2 lp = (pq & 1) ? __builtin_amdgcn_cvt_pk_f32_fp8(bw, true) : __builtin_amdgcn_cvt_pk_f32_fp8(bw, false);
;                             h0 = __uint_as_float(a << 16) + lp.x * 0.00390625f; h1 = __uint_as_float(a & 0xffff0000u) + lp.y * 0.00390625f; }
;                         const float o0 = h0 + acc[ai][bj][mh + m][pq >> 1][(2 * pq) & 3] * rs1, o1 = h1 + acc[ai][bj][mh + m][pq >> 1][(2 * pq + 1) & 3] * rs1;
;                         sq += o0 * o0 + o1 * o1;
;                         const unsigned hi = cvt_pk_bf16(o0, o1);
;                         hw[pq] = hi;
;                         const float r0 = __builtin_amdgcn_fmed3f((o0 - __uint_as_float(hi << 16)) * 256.0f, -448.0f, 448.0f), r1 = __builtin_amdgcn_fmed3f((o1 - __uint_as_float(hi & 0xffff0000u)) * 256.0f, -448.0f, 448.0f);
;                         lw[pq >> 1] = (pq & 1) ? __builtin_amdgcn_cvt_pk_fp8_f32(r0, r1, lw[pq >> 1], true) : __builtin_amdgcn_cvt_pk_fp8_f32(r0, r1, lw[pq >> 1], false);
;                     }
;                     *(u32x4*)(Hb + idx) = (u32x4){hw[0], hw[1], hw[2], hw[3]}; *(u32x2*)(Hl + idx) = (u32x2){(unsigned)lw[0], (unsigned)lw[1]}; }
;                 sq += __shfl_xor(sq, 16); sq += __shfl_xor(sq, 32); if (fq == 0) ss[(size_t)row * 32 + u.pn * 4 + wc] = sq; }
	v_fma_f32 v0, v128, v174, v184
	v_fma_f32 v128, v129, v174, v185
	v_fma_f32 v129, v130, v174, v186
	v_fmac_f32_e32 v187, v131, v174
	v_fma_f32 v130, v124, v174, v192
	v_fma_f32 v131, v125, v174, v193
	v_fma_f32 v182, v126, v174, v194
	v_fmac_f32_e32 v195, v127, v174
	v_fma_f32 v184, v120, v174, v196
	v_mul_f32_e32 v120, v128, v128
	v_cvt_pk_bf16_f32 v124, v0, v128
	v_cvt_pk_bf16_f32 v125, v129, v187
	v_cvt_pk_bf16_f32 v126, v130, v131
	v_cvt_pk_bf16_f32 v127, v182, v195
	v_fmac_f32_e32 v120, v0, v0
	v_and_b32_e32 v193, 0xffff0000, v124
	v_lshlrev_b32_e32 v194, 16, v124
	v_and_b32_e32 v210, 0xffff0000, v126
	v_lshlrev_b32_e32 v211, 16, v126
	v_lshlrev_b32_e32 v212, 16, v127
	v_and_b32_e32 v213, 0xffff0000, v127
	global_store_dwordx4 v[206:207], v[124:127], off
	v_sub_f32_e32 v0, v0, v194
	v_mul_f32_e32 v0, 0x43800000, v0
	v_sub_f32_e32 v124, v128, v193
	v_sub_f32_e32 v127, v131, v210
	v_sub_f32_e32 v128, v130, v211
	v_mul_f32_e32 v124, 0x43800000, v124
	v_mul_f32_e32 v127, 0x43800000, v127
	v_mul_f32_e32 v128, 0x43800000, v128
	v_med3_f32 v124, v124, s68, v235
	v_med3_f32 v0, v0, s68, v235
	v_med3_f32 v127, v127, s68, v235
	v_med3_f32 v128, v128, s68, v235
	v_fma_f32 v121, v121, v174, v197
	v_mul_f32_e32 v185, v187, v187
	v_mul_f32_e32 v186, v131, v131
	v_lshlrev_b32_e32 v196, 16, v125
	v_and_b32_e32 v197, 0xffff0000, v125
	v_cvt_pk_fp8_f32 v180, v0, v124
	v_cvt_pk_fp8_f32 v181, v128, v127
	v_fmac_f32_e32 v185, v129, v129
	v_fmac_f32_e32 v186, v130, v130
	v_sub_f32_e32 v125, v129, v196
	v_sub_f32_e32 v126, v187, v197
	v_sub_f32_e32 v129, v182, v212
	v_sub_f32_e32 v130, v195, v213
	v_mul_f32_e32 v125, 0x43800000, v125
	v_mul_f32_e32 v126, 0x43800000, v126
	v_mul_f32_e32 v129, 0x43800000, v129
	v_mul_f32_e32 v130, 0x43800000, v130
	v_med3_f32 v125, v125, s68, v235
	v_med3_f32 v126, v126, s68, v235
	v_med3_f32 v0, v129, s68, v235
	v_med3_f32 v124, v130, s68, v235
	v_cvt_pk_fp8_f32 v180, v125, v126 op_sel:[0,0,1]
	v_cvt_pk_fp8_f32 v181, v0, v124 op_sel:[0,0,1]
	v_add_f32_e32 v120, v120, v185
	v_add_f32_e32 v0, v120, v186
	v_mul_f32_e32 v192, v121, v121
	global_store_dwordx2 v[208:209], v[180:181], off
	v_cvt_pk_bf16_f32 v120, v184, v121
	v_mul_f32_e32 v191, v195, v195
	v_and_b32_e32 v124, 0xffff0000, v120
	v_sub_f32_e32 v121, v121, v124
	v_lshlrev_b32_e32 v124, 16, v120
	v_sub_f32_e32 v124, v184, v124
	v_mul_f32_e32 v121, 0x43800000, v121
	v_mul_f32_e32 v124, 0x43800000, v124
	v_fmac_f32_e32 v191, v182, v182
	v_med3_f32 v121, v121, s68, v235
	v_med3_f32 v125, v124, s68, v235
	v_mov_b32_e32 v124, v1
	v_fmac_f32_e32 v199, v123, v174
	v_fmac_f32_e32 v192, v184, v184
	v_add_f32_e32 v0, v191, v0
	v_cvt_pk_fp8_f32 v124, v125, v121
	v_fma_f32 v122, v122, v174, v198
	v_mul_f32_e32 v121, v199, v199
	v_add_f32_e32 v0, v192, v0
	v_fmac_f32_e32 v121, v122, v122
	v_add_f32_e32 v0, v121, v0
	v_cvt_pk_bf16_f32 v121, v122, v199
	v_fma_f32 v117, v117, v174, v201
	v_lshlrev_b32_e32 v123, 16, v121
	v_sub_f32_e32 v122, v122, v123
	v_and_b32_e32 v123, 0xffff0000, v121
	v_sub_f32_e32 v123, v199, v123
	v_mul_f32_e32 v122, 0x43800000, v122
	v_mul_f32_e32 v123, 0x43800000, v123
	v_med3_f32 v122, v122, s68, v235
	v_med3_f32 v123, v123, s68, v235
	v_cvt_pk_fp8_f32 v124, v122, v123 op_sel:[0,0,1]
	v_fma_f32 v116, v116, v174, v200
	v_mul_f32_e32 v122, v117, v117
	v_fmac_f32_e32 v122, v116, v116
	v_add_f32_e32 v0, v122, v0
	v_cvt_pk_bf16_f32 v122, v116, v117
	v_mov_b32_e32 v125, v1
	v_and_b32_e32 v123, 0xffff0000, v122
	v_sub_f32_e32 v117, v117, v123
	v_lshlrev_b32_e32 v123, 16, v122
	v_sub_f32_e32 v116, v116, v123
	v_mul_f32_e32 v117, 0x43800000, v117
	v_mul_f32_e32 v116, 0x43800000, v116
	v_med3_f32 v117, v117, s68, v235
	v_med3_f32 v116, v116, s68, v235
	v_fmac_f32_e32 v203, v119, v174
	v_cvt_pk_fp8_f32 v125, v116, v117
	v_fma_f32 v116, v118, v174, v202
	v_mul_f32_e32 v117, v203, v203
	v_fmac_f32_e32 v117, v116, v116
	v_add_f32_e32 v117, v117, v0
	v_cvt_pk_bf16_f32 v123, v116, v203
	v_and_b32_e32 v119, 64, v226
	v_lshlrev_b32_e32 v0, 16, v123
	v_sub_f32_e32 v0, v116, v0
	v_mul_f32_e32 v0, 0x43800000, v0
	v_med3_f32 v116, v0, s68, v235
	v_and_b32_e32 v0, 0xffff0000, v123
	v_sub_f32_e32 v118, v203, v0
	v_xor_b32_e32 v0, 16, v226
	v_add_u32_e32 v119, 64, v119
	v_cmp_lt_i32_e32 vcc, v0, v119
	v_mul_f32_e32 v118, 0x43800000, v118
	v_med3_f32 v118, v118, s68, v235
	v_cndmask_b32_e32 v0, v226, v0, vcc
	v_lshlrev_b32_e32 v0, 2, v0
	ds_bpermute_b32 v126, v0, v117
	v_cvt_pk_fp8_f32 v125, v116, v118 op_sel:[0,0,1]
	s_waitcnt lgkmcnt(0)
	v_add_f32_e32 v116, v117, v126
	v_xor_b32_e32 v117, 32, v226
	v_cmp_lt_i32_e32 vcc, v117, v119
	v_lshl_add_u64 v[118:119], v[204:205], 1, s[42:43]
	global_store_dwordx4 v[118:119], v[120:123], off
	v_cndmask_b32_e32 v117, v226, v117, vcc
	v_lshlrev_b32_e32 v174, 2, v117
	ds_bpermute_b32 v117, v174, v116
	v_lshl_add_u64 v[118:119], s[44:45], 0, v[204:205]
	global_store_dwordx2 v[118:119], v[124:125], off
	s_and_saveexec_b64 s[2:3], s[38:39]
	v_readlane_b32 s74, v255, 12
	v_readlane_b32 s76, v255, 14
	v_readlane_b32 s72, v255, 11
	v_readlane_b32 s75, v255, 13
	v_readlane_b32 s77, v255, 15
	v_readlane_b32 s73, v255, 16
	s_cbranch_execz .LBB0_1042
	s_waitcnt lgkmcnt(0)
	v_add_f32_e32 v118, v116, v117
	s_lshl_b32 s20, s56, 2
	v_lshlrev_b64 v[116:117], 7, v[164:165]
	s_ashr_i32 s21, s20, 31
	v_lshl_add_u64 v[116:117], s[8:9], 0, v[116:117]
	v_lshl_add_u64 v[116:117], s[20:21], 2, v[116:117]
	s_lshl_b32 s18, s37, 2
	v_lshl_add_u64 v[116:117], v[116:117], 0, s[18:19]
	global_store_dword v[116:117], v118, off

;     __device__ __forceinline__ void core(const f32x4 (&acc)[2][2][4][2], const Unit& u, int wr, int wc, int fr, int fq, const float (&rsc)[2][4]) const {
;     ...
;             u32x4 va[MB][2]; u32x2 vb[MB][2];
;             f32x4 xa[MB][2], xb[MB][2];
; #pragma unroll
;             for (int m = 0; m < MB; ++m)
; #pragma unroll
;                 for (int bj = 0; bj < 2; ++bj) { const size_t idx = (size_t)(row0 + ai * HALF + (mh + m) * 16) * D + col0 + bj * HALF;
;                     if (F32IN) { xa[m][bj] = *(const f32x4*)(Xin + idx); xb[m][bj] = *(const f32x4*)(Xin + idx + 4); }
;                     else { va[m][bj] = *(const u32x4*)(Hb + idx); vb[m][bj] = *(const u32x2*)(Hl + idx); } }
; #pragma unroll
;             for (int m = 0; m < MB; ++m) { const int row = row0 + ai * HALF + (mh + m) * 16; float sq = 0.f;
;                 const float rs1 = rsc[ai][mh + m];
; #pragma unroll
;                 for (int bj = 0; bj < 2; ++bj) { const size_t idx = (size_t)row * D + col0 + bj * HALF;
;                     unsigned hw[4]; int lw[2] = {0, 0};
; #pragma unroll
;                     for (int pq = 0; pq < 4; ++pq) {
;                         float h0, h1;
;                         if (F32IN) { h0 = (pq < 2) ? xa[m][bj][2 * pq] : xb[m][bj][2 * pq - 4]; h1 = (pq < 2) ? xa[m][bj][2 * pq + 1] : xb[m][bj][2 * pq - 3]; }
;                         else { const unsigned a = va[m][bj][pq]; const int bw = (int)vb[m][bj][pq >> 1]; const hf32x2 lp = (pq & 1) ? __builtin_amdgcn_cvt_pk_f32_fp8(bw, true) : __builtin_amdgcn_cvt_pk_f32_fp8(bw, false);
;                             h0 = __uint_as_float(a << 16) + lp.x * 0.00390625f; h1 = __uint_as_float(a & 0xffff0000u) + lp.y * 0.00390625f; }
;                         const float o0 = h0 + acc[ai][bj][mh + m][pq >> 1][(2 * pq) & 3] * rs1, o1 = h1 + acc[ai][bj][mh + m][pq >> 1][(2 * pq + 1) & 3] * rs1;
;                         sq += o0 * o0 + o1 * o1;
;                         const unsigned hi = cvt_pk_bf16(o0, o1);
;                         hw[pq] = hi;
;                         const float r0 = __builtin_amdgcn_fmed3f((o0 - __uint_as_float(hi << 16)) * 256.0f, -448.0f, 448.0f), r1 = __builtin_amdgcn_fmed3f((o1 - __uint_as_float(hi & 0xffff0000u)) * 256.0f, -448.0f, 448.0f);
.LBB0_1044:
	s_or_b64 exec, exec, s[2:3]
	v_or_b32_e32 v130, 32, v164
	v_ashrrev_i32_e32 v131, 31, v130
	s_waitcnt lgkmcnt(0)
	v_or_b32_e32 v128, 48, v164
	v_ashrrev_i32_e32 v129, 31, v128
	s_waitcnt vmcnt(8)
	v_mov_b32_e32 v124, v214
	v_mov_b32_e32 v125, v215
	v_mov_b32_e32 v126, v216
	v_mov_b32_e32 v127, v217
	v_mov_b32_e32 v134, v218
	v_mov_b32_e32 v135, v219
	v_mov_b32_e32 v136, v220
	v_mov_b32_e32 v137, v221
	v_mov_b32_e32 v116, v236
	v_mov_b32_e32 v117, v237
	v_mov_b32_e32 v118, v238
	v_mov_b32_e32 v119, v239
	v_mov_b32_e32 v120, v240
	v_mov_b32_e32 v121, v241
	v_mov_b32_e32 v122, v242
	v_mov_b32_e32 v123, v243
	v_mov_b32_e32 v108, v244
	v_mov_b32_e32 v109, v245
	v_mov_b32_e32 v110, v246
	v_mov_b32_e32 v111, v247
	v_mov_b32_e32 v112, v248
	v_mov_b32_e32 v113, v249
	v_mov_b32_e32 v114, v250
	v_mov_b32_e32 v115, v251
	v_mov_b32_e32 v100, v148
	v_mov_b32_e32 v101, v149
	v_mov_b32_e32 v102, v150
	v_mov_b32_e32 v103, v151
	v_mov_b32_e32 v104, v152
	v_mov_b32_e32 v105, v153
	v_mov_b32_e32 v106, v154
	v_mov_b32_e32 v107, v155
	v_add_u32_e32 v252, 0x80, v164
	v_ashrrev_i32_e32 v253, 31, v252
	v_lshlrev_b64 v[252:253], 13, v[252:253]
	v_lshl_add_u64 v[252:253], v[166:167], 0, v[252:253]
	global_load_dwordx4 v[214:217], v[252:253], off offset:16
	global_load_dwordx4 v[218:221], v[252:253], off
	global_load_dwordx4 v[236:239], v[252:253], off offset:528
	global_load_dwordx4 v[240:243], v[252:253], off offset:512
	v_add_u32_e32 v252, 0x90, v164
	v_ashrrev_i32_e32 v253, 31, v252
	v_lshlrev_b64 v[252:253], 13, v[252:253]
	v_lshl_add_u64 v[252:253], v[166:167], 0, v[252:253]
	global_load_dwordx4 v[244:247], v[252:253], off offset:16
	global_load_dwordx4 v[248:251], v[252:253], off
	global_load_dwordx4 v[148:151], v[252:253], off offset:528
	global_load_dwordx4 v[152:155], v[252:253], off offset:512
	v_lshlrev_b64 v[132:133], 11, v[130:131]
	v_lshl_add_u64 v[132:133], v[132:133], 0, v[162:163]
	s_nop 0
	v_fma_f32 v93, v93, v170, v125
	s_nop 0
	v_fma_f32 v134, v96, v170, v134
	v_fma_f32 v97, v97, v170, v135
	v_cvt_pk_bf16_f32 v96, v134, v97
	v_mul_f32_e32 v135, v97, v97
	v_and_b32_e32 v138, 0xffff0000, v96
	v_sub_f32_e32 v97, v97, v138
	v_lshlrev_b32_e32 v138, 16, v96
	v_fmac_f32_e32 v135, v134, v134
	v_sub_f32_e32 v134, v134, v138
	v_mul_f32_e32 v97, 0x43800000, v97
	v_mul_f32_e32 v134, 0x43800000, v134
	v_med3_f32 v97, v97, s68, v235
	v_med3_f32 v138, v134, s68, v235
	v_mov_b32_e32 v134, v1
	v_fmac_f32_e32 v137, v99, v170
	v_cvt_pk_fp8_f32 v134, v138, v97
	v_fma_f32 v98, v98, v170, v136
	v_mul_f32_e32 v97, v137, v137
	v_fmac_f32_e32 v97, v98, v98
	v_add_f32_e32 v99, v135, v97
	v_cvt_pk_bf16_f32 v97, v98, v137
	v_fma_f32 v92, v92, v170, v124
	v_lshlrev_b32_e32 v135, 16, v97
	v_sub_f32_e32 v98, v98, v135
	v_and_b32_e32 v135, 0xffff0000, v97
	v_sub_f32_e32 v135, v137, v135
	v_mul_f32_e32 v98, 0x43800000, v98
	v_mul_f32_e32 v135, 0x43800000, v135
	v_med3_f32 v98, v98, s68, v235
	v_med3_f32 v135, v135, s68, v235
	v_cvt_pk_fp8_f32 v134, v98, v135 op_sel:[0,0,1]
	v_mul_f32_e32 v98, v93, v93
	v_fmac_f32_e32 v98, v92, v92
	v_add_f32_e32 v99, v99, v98
	v_cvt_pk_bf16_f32 v98, v92, v93
	v_mov_b32_e32 v135, v1
	v_and_b32_e32 v124, 0xffff0000, v98
	v_sub_f32_e32 v93, v93, v124
	v_lshlrev_b32_e32 v124, 16, v98
	v_sub_f32_e32 v92, v92, v124
	v_mul_f32_e32 v93, 0x43800000, v93
	v_mul_f32_e32 v92, 0x43800000, v92
	v_med3_f32 v93, v93, s68, v235
	v_med3_f32 v92, v92, s68, v235
	v_fmac_f32_e32 v127, v95, v170
	v_cvt_pk_fp8_f32 v135, v92, v93
	v_fma_f32 v92, v94, v170, v126
	v_mul_f32_e32 v93, v127, v127
	v_fmac_f32_e32 v93, v92, v92
	v_add_f32_e32 v94, v93, v99
	v_cvt_pk_bf16_f32 v99, v92, v127
	s_nop 0
	v_fma_f32 v89, v89, v170, v121
	v_lshlrev_b32_e32 v93, 16, v99
	v_sub_f32_e32 v92, v92, v93
	v_and_b32_e32 v93, 0xffff0000, v99
	v_sub_f32_e32 v93, v127, v93
	v_mul_f32_e32 v92, 0x43800000, v92
	v_mul_f32_e32 v93, 0x43800000, v93
	v_med3_f32 v92, v92, s68, v235
	v_med3_f32 v93, v93, s68, v235
	v_cvt_pk_fp8_f32 v135, v92, v93 op_sel:[0,0,1]
	v_lshl_add_u64 v[92:93], v[132:133], 1, s[42:43]
	global_store_dwordx4 v[92:93], v[96:99], off
	v_lshl_add_u64 v[92:93], s[44:45], 0, v[132:133]
	global_store_dwordx2 v[92:93], v[134:135], off
	v_fma_f32 v92, v88, v170, v120
	v_mul_f32_e32 v88, v89, v89
	v_fmac_f32_e32 v88, v92, v92
	v_add_f32_e32 v93, v88, v94
	v_cvt_pk_bf16_f32 v88, v92, v89
	v_fmac_f32_e32 v123, v91, v170
	v_and_b32_e32 v94, 0xffff0000, v88
	v_sub_f32_e32 v89, v89, v94
	v_lshlrev_b32_e32 v94, 16, v88
	v_sub_f32_e32 v92, v92, v94
	v_mul_f32_e32 v89, 0x43800000, v89
	v_mul_f32_e32 v92, 0x43800000, v92
	v_med3_f32 v89, v89, s68, v235
	v_med3_f32 v94, v92, s68, v235
	v_mov_b32_e32 v92, v1
	v_cvt_pk_fp8_f32 v92, v94, v89
	v_fma_f32 v90, v90, v170, v122
	v_mul_f32_e32 v89, v123, v123
	v_fmac_f32_e32 v89, v90, v90
	v_add_f32_e32 v91, v89, v93
	v_cvt_pk_bf16_f32 v89, v90, v123
	v_fma_f32 v85, v85, v170, v117
	v_lshlrev_b32_e32 v93, 16, v89
	v_sub_f32_e32 v90, v90, v93
	v_and_b32_e32 v93, 0xffff0000, v89
	v_sub_f32_e32 v93, v123, v93
	v_mul_f32_e32 v90, 0x43800000, v90
	v_mul_f32_e32 v93, 0x43800000, v93
	v_med3_f32 v90, v90, s68, v235
	v_med3_f32 v93, v93, s68, v235
	v_cvt_pk_fp8_f32 v92, v90, v93 op_sel:[0,0,1]
	v_fma_f32 v84, v84, v170, v116
	v_mul_f32_e32 v90, v85, v85
	v_fmac_f32_e32 v90, v84, v84
	v_add_f32_e32 v91, v90, v91
	v_cvt_pk_bf16_f32 v90, v84, v85
	v_fmac_f32_e32 v119, v87, v170
	v_and_b32_e32 v93, 0xffff0000, v90
	v_sub_f32_e32 v85, v85, v93
	v_lshlrev_b32_e32 v93, 16, v90
	v_sub_f32_e32 v84, v84, v93
	v_mul_f32_e32 v85, 0x43800000, v85
	v_mul_f32_e32 v84, 0x43800000, v84
	v_med3_f32 v85, v85, s68, v235
	v_med3_f32 v84, v84, s68, v235
	v_mov_b32_e32 v93, v1
	v_cvt_pk_fp8_f32 v93, v84, v85
	v_fma_f32 v84, v86, v170, v118
	v_mul_f32_e32 v85, v119, v119
	v_fmac_f32_e32 v85, v84, v84
	v_add_f32_e32 v86, v85, v91
	v_cvt_pk_bf16_f32 v91, v84, v119
	v_or_b32_e32 v132, 0x80, v132
	v_lshlrev_b32_e32 v85, 16, v91
	v_sub_f32_e32 v84, v84, v85
	v_and_b32_e32 v85, 0xffff0000, v91
	v_sub_f32_e32 v85, v119, v85
	v_mul_f32_e32 v84, 0x43800000, v84
	v_mul_f32_e32 v85, 0x43800000, v85
	v_med3_f32 v84, v84, s68, v235
	v_med3_f32 v85, v85, s68, v235
	v_cvt_pk_fp8_f32 v93, v84, v85 op_sel:[0,0,1]
	v_lshl_add_u64 v[84:85], v[132:133], 1, s[42:43]
	global_store_dwordx4 v[84:85], v[88:91], off
	v_lshl_add_u64 v[84:85], s[44:45], 0, v[132:133]
	global_store_dwordx2 v[84:85], v[92:93], off
	ds_bpermute_b32 v84, v0, v86
	s_waitcnt lgkmcnt(0)
	v_add_f32_e32 v84, v86, v84
	ds_bpermute_b32 v85, v174, v84
	s_and_saveexec_b64 s[2:3], s[38:39]
	s_cbranch_execz .LBB0_1046
	s_waitcnt lgkmcnt(0)
	v_add_f32_e32 v86, v84, v85
	s_lshl_b32 s20, s56, 2
	v_lshlrev_b64 v[84:85], 7, v[130:131]
	s_ashr_i32 s21, s20, 31
	v_lshl_add_u64 v[84:85], s[8:9], 0, v[84:85]
	v_lshl_add_u64 v[84:85], s[20:21], 2, v[84:85]
	s_lshl_b32 s18, s37, 2
	v_lshl_add_u64 v[84:85], v[84:85], 0, s[18:19]
	global_store_dword v[84:85], v86, off
; __device__ __forceinline__ unsigned cvt_pk_bf16(float lo, float hi) { unsigned r; asm volatile("v_cvt_pk_bf16_f32 %0, %1, %2" : "=v"(r) : "v"(lo), "v"(hi)); return r; }
;     __device__ __forceinline__ void core(const f32x4 (&acc)[2][2][4][2], const Unit& u, int wr, int wc, int fr, int fq, const float (&rsc)[2][4]) const {
;     ...
;             for (int m = 0; m < MB; ++m) { const int row = row0 + ai * HALF + (mh + m) * 16; float sq = 0.f;
;                 const float rs1 = rsc[ai][mh + m];
; #pragma unroll
;                 for (int bj = 0; bj < 2; ++bj) { const size_t idx = (size_t)row * D + col0 + bj * HALF;
;                     unsigned hw[4]; int lw[2] = {0, 0};
; #pragma unroll
;                     for (int pq = 0; pq < 4; ++pq) {
;                         float h0, h1;
;                         if (F32IN) { h0 = (pq < 2) ? xa[m][bj][2 * pq] : xb[m][bj][2 * pq - 4]; h1 = (pq < 2) ? xa[m][bj][2 * pq + 1] : xb[m][bj][2 * pq - 3]; }
;                         else { const unsigned a = va[m][bj][pq]; const int bw = (int)vb[m][bj][pq >> 1]; const hf32x2 lp = (pq & 1) ? __builtin_amdgcn_cvt_pk_f32_fp8(bw, true) : __builtin_amdgcn_cvt_pk_f32_fp8(bw, false);
;                             h0 = __uint_as_float(a << 16) + lp.x * 0.00390625f; h1 = __uint_as_float(a & 0xffff0000u) + lp.y * 0.00390625f; }
;                         const float o0 = h0 + acc[ai][bj][mh + m][pq >> 1][(2 * pq) & 3] * rs1, o1 = h1 + acc[ai][bj][mh + m][pq >> 1][(2 * pq + 1) & 3] * rs1;
;                         sq += o0 * o0 + o1 * o1;
;                         const unsigned hi = cvt_pk_bf16(o0, o1);
;                         hw[pq] = hi;
;                         const float r0 = __builtin_amdgcn_fmed3f((o0 - __uint_as_float(hi << 16)) * 256.0f, -448.0f, 448.0f), r1 = __builtin_amdgcn_fmed3f((o1 - __uint_as_float(hi & 0xffff0000u)) * 256.0f, -448.0f, 448.0f);
;                         lw[pq >> 1] = (pq & 1) ? __builtin_amdgcn_cvt_pk_fp8_f32(r0, r1, lw[pq >> 1], true) : __builtin_amdgcn_cvt_pk_fp8_f32(r0, r1, lw[pq >> 1], false);
;                     }
;                     *(u32x4*)(Hb + idx) = (u32x4){hw[0], hw[1], hw[2], hw[3]}; *(u32x2*)(Hl + idx) = (u32x2){(unsigned)lw[0], (unsigned)lw[1]}; }
;                 sq += __shfl_xor(sq, 16); sq += __shfl_xor(sq, 32); if (fq == 0) ss[(size_t)row * 32 + u.pn * 4 + wc] = sq; }
.LBB0_1046:
	s_or_b64 exec, exec, s[2:3]
	s_nop 0
	v_fma_f32 v86, v80, v171, v112
	v_fma_f32 v81, v81, v171, v113
	v_cvt_pk_bf16_f32 v80, v86, v81
	v_mul_f32_e32 v87, v81, v81
	v_and_b32_e32 v88, 0xffff0000, v80
	v_sub_f32_e32 v81, v81, v88
	v_lshlrev_b32_e32 v88, 16, v80
	v_fmac_f32_e32 v87, v86, v86
	v_sub_f32_e32 v86, v86, v88
	v_mul_f32_e32 v81, 0x43800000, v81
	v_mul_f32_e32 v86, 0x43800000, v86
	v_med3_f32 v81, v81, s68, v235
	v_med3_f32 v88, v86, s68, v235
	v_mov_b32_e32 v86, v1
	v_fmac_f32_e32 v115, v83, v171
	v_cvt_pk_fp8_f32 v86, v88, v81
	v_fma_f32 v82, v82, v171, v114
	v_mul_f32_e32 v81, v115, v115
	v_fmac_f32_e32 v81, v82, v82
	v_add_f32_e32 v83, v87, v81
	v_cvt_pk_bf16_f32 v81, v82, v115
	v_fma_f32 v77, v77, v171, v109
	v_lshlrev_b32_e32 v87, 16, v81
	v_sub_f32_e32 v82, v82, v87
	v_and_b32_e32 v87, 0xffff0000, v81
	v_sub_f32_e32 v87, v115, v87
	v_mul_f32_e32 v82, 0x43800000, v82
	v_mul_f32_e32 v87, 0x43800000, v87
	v_med3_f32 v82, v82, s68, v235
	v_med3_f32 v87, v87, s68, v235
	v_cvt_pk_fp8_f32 v86, v82, v87 op_sel:[0,0,1]
	v_fma_f32 v76, v76, v171, v108
	v_mul_f32_e32 v82, v77, v77
	v_fmac_f32_e32 v82, v76, v76
	v_add_f32_e32 v83, v83, v82
	v_cvt_pk_bf16_f32 v82, v76, v77
	v_fmac_f32_e32 v111, v79, v171
	v_and_b32_e32 v87, 0xffff0000, v82
	v_sub_f32_e32 v77, v77, v87
	v_lshlrev_b32_e32 v87, 16, v82
	v_sub_f32_e32 v76, v76, v87
	v_mul_f32_e32 v77, 0x43800000, v77
	v_mul_f32_e32 v76, 0x43800000, v76
	v_med3_f32 v77, v77, s68, v235
	v_med3_f32 v76, v76, s68, v235
	v_mov_b32_e32 v87, v1
	v_cvt_pk_fp8_f32 v87, v76, v77
	v_fma_f32 v76, v78, v171, v110
	v_mul_f32_e32 v77, v111, v111
	v_fmac_f32_e32 v77, v76, v76
	v_add_f32_e32 v78, v77, v83
	v_cvt_pk_bf16_f32 v83, v76, v111
	s_waitcnt lgkmcnt(0)
	v_lshlrev_b64 v[84:85], 11, v[128:129]
	v_lshlrev_b32_e32 v77, 16, v83
	v_sub_f32_e32 v76, v76, v77
	v_and_b32_e32 v77, 0xffff0000, v83
	v_sub_f32_e32 v77, v111, v77
	v_mul_f32_e32 v76, 0x43800000, v76
	v_mul_f32_e32 v77, 0x43800000, v77
	v_med3_f32 v76, v76, s68, v235
	v_med3_f32 v77, v77, s68, v235
	v_cvt_pk_fp8_f32 v87, v76, v77 op_sel:[0,0,1]
	v_lshl_add_u64 v[84:85], v[84:85], 0, v[162:163]
	v_lshl_add_u64 v[76:77], v[84:85], 1, s[42:43]
	global_store_dwordx4 v[76:77], v[80:83], off
	v_lshl_add_u64 v[76:77], s[44:45], 0, v[84:85]
	s_nop 0
	v_fma_f32 v73, v73, v171, v105
	global_store_dwordx2 v[76:77], v[86:87], off
	v_fma_f32 v76, v72, v171, v104
	v_mul_f32_e32 v72, v73, v73
	v_fmac_f32_e32 v72, v76, v76
	v_add_f32_e32 v77, v72, v78
	v_cvt_pk_bf16_f32 v72, v76, v73
	v_fmac_f32_e32 v107, v75, v171
	v_and_b32_e32 v78, 0xffff0000, v72
	v_sub_f32_e32 v73, v73, v78
	v_lshlrev_b32_e32 v78, 16, v72
	v_sub_f32_e32 v76, v76, v78
	v_mul_f32_e32 v73, 0x43800000, v73
	v_mul_f32_e32 v76, 0x43800000, v76
	v_med3_f32 v73, v73, s68, v235
	v_med3_f32 v78, v76, s68, v235
	v_mov_b32_e32 v76, v1
	v_cvt_pk_fp8_f32 v76, v78, v73
	v_fma_f32 v74, v74, v171, v106
	v_mul_f32_e32 v73, v107, v107
	v_fmac_f32_e32 v73, v74, v74
	v_add_f32_e32 v75, v73, v77
	v_cvt_pk_bf16_f32 v73, v74, v107
	v_fma_f32 v69, v69, v171, v101
	v_lshlrev_b32_e32 v77, 16, v73
	v_sub_f32_e32 v74, v74, v77
	v_and_b32_e32 v77, 0xffff0000, v73
	v_sub_f32_e32 v77, v107, v77
	v_mul_f32_e32 v74, 0x43800000, v74
	v_mul_f32_e32 v77, 0x43800000, v77
	v_med3_f32 v74, v74, s68, v235
	v_med3_f32 v77, v77, s68, v235
	v_cvt_pk_fp8_f32 v76, v74, v77 op_sel:[0,0,1]
	v_fma_f32 v68, v68, v171, v100
	v_mul_f32_e32 v74, v69, v69
	v_fmac_f32_e32 v74, v68, v68
	v_add_f32_e32 v75, v74, v75
	v_cvt_pk_bf16_f32 v74, v68, v69
	v_fmac_f32_e32 v103, v71, v171
	v_and_b32_e32 v77, 0xffff0000, v74
	v_sub_f32_e32 v69, v69, v77
	v_lshlrev_b32_e32 v77, 16, v74
	v_sub_f32_e32 v68, v68, v77
	v_mul_f32_e32 v69, 0x43800000, v69
	v_mul_f32_e32 v68, 0x43800000, v68
	v_med3_f32 v69, v69, s68, v235
	v_med3_f32 v68, v68, s68, v235
	v_mov_b32_e32 v77, v1
	v_cvt_pk_fp8_f32 v77, v68, v69
	v_fma_f32 v68, v70, v171, v102
	v_mul_f32_e32 v69, v103, v103
	v_fmac_f32_e32 v69, v68, v68
	v_add_f32_e32 v69, v69, v75
	v_cvt_pk_bf16_f32 v75, v68, v103
	ds_bpermute_b32 v71, v0, v69
	v_lshlrev_b32_e32 v70, 16, v75
	v_sub_f32_e32 v68, v68, v70
	v_and_b32_e32 v70, 0xffff0000, v75
	v_sub_f32_e32 v70, v103, v70
	v_mul_f32_e32 v68, 0x43800000, v68
	v_mul_f32_e32 v70, 0x43800000, v70
	v_med3_f32 v68, v68, s68, v235
	v_med3_f32 v70, v70, s68, v235
	v_cvt_pk_fp8_f32 v77, v68, v70 op_sel:[0,0,1]
	s_waitcnt lgkmcnt(0)
	v_add_f32_e32 v68, v69, v71
	ds_bpermute_b32 v69, v174, v68
	v_or_b32_e32 v84, 0x80, v84
	v_lshl_add_u64 v[70:71], v[84:85], 1, s[42:43]
	global_store_dwordx4 v[70:71], v[72:75], off
	v_lshl_add_u64 v[70:71], s[44:45], 0, v[84:85]
	global_store_dwordx2 v[70:71], v[76:77], off
	s_and_saveexec_b64 s[2:3], s[38:39]
	s_cbranch_execz .LBB0_1048
	s_waitcnt lgkmcnt(0)
	v_add_f32_e32 v70, v68, v69
	s_lshl_b32 s20, s56, 2
	v_lshlrev_b64 v[68:69], 7, v[128:129]
	s_ashr_i32 s21, s20, 31
	v_lshl_add_u64 v[68:69], s[8:9], 0, v[68:69]
	v_lshl_add_u64 v[68:69], s[20:21], 2, v[68:69]
	s_lshl_b32 s18, s37, 2
	v_lshl_add_u64 v[68:69], v[68:69], 0, s[18:19]
	global_store_dword v[68:69], v70, off
;     __device__ __forceinline__ void core(const f32x4 (&acc)[2][2][4][2], const Unit& u, int wr, int wc, int fr, int fq, const float (&rsc)[2][4]) const {
;     ...
; #pragma unroll
;             for (int m = 0; m < MB; ++m)
; #pragma unroll
;                 for (int bj = 0; bj < 2; ++bj) { const size_t idx = (size_t)(row0 + ai * HALF + (mh + m) * 16) * D + col0 + bj * HALF;
;                     if (F32IN) { xa[m][bj] = *(const f32x4*)(Xin + idx); xb[m][bj] = *(const f32x4*)(Xin + idx + 4); }
;                     else { va[m][bj] = *(const u32x4*)(Hb + idx); vb[m][bj] = *(const u32x2*)(Hl + idx); } }
; #pragma unroll
;             for (int m = 0; m < MB; ++m) { const int row = row0 + ai * HALF + (mh + m) * 16; float sq = 0.f;
;                 const float rs1 = rsc[ai][mh + m];
; #pragma unroll
;                 for (int bj = 0; bj < 2; ++bj) { const size_t idx = (size_t)row * D + col0 + bj * HALF;
;                     unsigned hw[4]; int lw[2] = {0, 0};
; #pragma unroll
;                     for (int pq = 0; pq < 4; ++pq) {
;                         float h0, h1;
;                         if (F32IN) { h0 = (pq < 2) ? xa[m][bj][2 * pq] : xb[m][bj][2 * pq - 4]; h1 = (pq < 2) ? xa[m][bj][2 * pq + 1] : xb[m][bj][2 * pq - 3]; }
;                         else { const unsigned a = va[m][bj][pq]; const int bw = (int)vb[m][bj][pq >> 1]; const hf32x2 lp = (pq & 1) ? __builtin_amdgcn_cvt_pk_f32_fp8(bw, true) : __builtin_amdgcn_cvt_pk_f32_fp8(bw, false);
;                             h0 = __uint_as_float(a << 16) + lp.x * 0.00390625f; h1 = __uint_as_float(a & 0xffff0000u) + lp.y * 0.00390625f; }
;                         const float o0 = h0 + acc[ai][bj][mh + m][pq >> 1][(2 * pq) & 3] * rs1, o1 = h1 + acc[ai][bj][mh + m][pq >> 1][(2 * pq + 1) & 3] * rs1;
;                         sq += o0 * o0 + o1 * o1;
;                         const unsigned hi = cvt_pk_bf16(o0, o1);
;                         hw[pq] = hi;
;                         const float r0 = __builtin_amdgcn_fmed3f((o0 - __uint_as_float(hi << 16)) * 256.0f, -448.0f, 448.0f), r1 = __builtin_amdgcn_fmed3f((o1 - __uint_as_float(hi & 0xffff0000u)) * 256.0f, -448.0f, 448.0f);
;                         lw[pq >> 1] = (pq & 1) ? __builtin_amdgcn_cvt_pk_fp8_f32(r0, r1, lw[pq >> 1], true) : __builtin_amdgcn_cvt_pk_fp8_f32(r0, r1, lw[pq >> 1], false);
;                     }
.LBB0_1048:
	s_or_b64 exec, exec, s[2:3]
	v_add_u32_e32 v98, 0x80, v164
	v_ashrrev_i32_e32 v99, 31, v98
	s_waitcnt lgkmcnt(0)
	v_add_u32_e32 v96, 0x90, v164
	v_ashrrev_i32_e32 v97, 31, v96
	s_waitcnt vmcnt(8)
	v_mov_b32_e32 v92, v214
	v_mov_b32_e32 v93, v215
	v_mov_b32_e32 v94, v216
	v_mov_b32_e32 v95, v217
	v_mov_b32_e32 v102, v218
	v_mov_b32_e32 v103, v219
	v_mov_b32_e32 v104, v220
	v_mov_b32_e32 v105, v221
	v_mov_b32_e32 v84, v236
	v_mov_b32_e32 v85, v237
	v_mov_b32_e32 v86, v238
	v_mov_b32_e32 v87, v239
	v_mov_b32_e32 v88, v240
	v_mov_b32_e32 v89, v241
	v_mov_b32_e32 v90, v242
	v_mov_b32_e32 v91, v243
	v_mov_b32_e32 v76, v244
	v_mov_b32_e32 v77, v245
	v_mov_b32_e32 v78, v246
	v_mov_b32_e32 v79, v247
	v_mov_b32_e32 v80, v248
	v_mov_b32_e32 v81, v249
	v_mov_b32_e32 v82, v250
	v_mov_b32_e32 v83, v251
	v_mov_b32_e32 v68, v148
	v_mov_b32_e32 v69, v149
	v_mov_b32_e32 v70, v150
	v_mov_b32_e32 v71, v151
	v_mov_b32_e32 v72, v152
	v_mov_b32_e32 v73, v153
	v_mov_b32_e32 v74, v154
	v_mov_b32_e32 v75, v155
	v_add_u32_e32 v252, 0xa0, v164
	v_ashrrev_i32_e32 v253, 31, v252
	v_lshlrev_b64 v[252:253], 13, v[252:253]
	v_lshl_add_u64 v[252:253], v[166:167], 0, v[252:253]
	global_load_dwordx4 v[214:217], v[252:253], off offset:16
	global_load_dwordx4 v[218:221], v[252:253], off
	global_load_dwordx4 v[236:239], v[252:253], off offset:528
	global_load_dwordx4 v[240:243], v[252:253], off offset:512
	v_add_u32_e32 v252, 0xb0, v164
	v_ashrrev_i32_e32 v253, 31, v252
	v_lshlrev_b64 v[252:253], 13, v[252:253]
	v_lshl_add_u64 v[252:253], v[166:167], 0, v[252:253]
	global_load_dwordx4 v[244:247], v[252:253], off offset:16
	global_load_dwordx4 v[248:251], v[252:253], off
	global_load_dwordx4 v[148:151], v[252:253], off offset:528
	global_load_dwordx4 v[152:155], v[252:253], off offset:512
	v_lshlrev_b64 v[100:101], 11, v[98:99]
	v_lshl_add_u64 v[100:101], v[100:101], 0, v[162:163]
	s_nop 0
	v_fma_f32 v61, v61, v168, v93
	s_nop 0
	v_fma_f32 v102, v64, v168, v102
	v_fma_f32 v65, v65, v168, v103
	v_cvt_pk_bf16_f32 v64, v102, v65
	v_mul_f32_e32 v103, v65, v65
	v_and_b32_e32 v106, 0xffff0000, v64
	v_sub_f32_e32 v65, v65, v106
	v_lshlrev_b32_e32 v106, 16, v64
	v_fmac_f32_e32 v103, v102, v102
	v_sub_f32_e32 v102, v102, v106
	v_mul_f32_e32 v65, 0x43800000, v65
	v_mul_f32_e32 v102, 0x43800000, v102
	v_med3_f32 v65, v65, s68, v235
	v_med3_f32 v106, v102, s68, v235
	v_mov_b32_e32 v102, v1
	v_fmac_f32_e32 v105, v67, v168
	v_cvt_pk_fp8_f32 v102, v106, v65
	v_fma_f32 v66, v66, v168, v104
	v_mul_f32_e32 v65, v105, v105
	v_fmac_f32_e32 v65, v66, v66
	v_add_f32_e32 v67, v103, v65
	v_cvt_pk_bf16_f32 v65, v66, v105
	v_fma_f32 v60, v60, v168, v92
	v_lshlrev_b32_e32 v103, 16, v65
	v_sub_f32_e32 v66, v66, v103
	v_and_b32_e32 v103, 0xffff0000, v65
	v_sub_f32_e32 v103, v105, v103
	v_mul_f32_e32 v66, 0x43800000, v66
	v_mul_f32_e32 v103, 0x43800000, v103
	v_med3_f32 v66, v66, s68, v235
	v_med3_f32 v103, v103, s68, v235
	v_cvt_pk_fp8_f32 v102, v66, v103 op_sel:[0,0,1]
	v_mul_f32_e32 v66, v61, v61
	v_fmac_f32_e32 v66, v60, v60
	v_add_f32_e32 v67, v67, v66
	v_cvt_pk_bf16_f32 v66, v60, v61
	v_mov_b32_e32 v103, v1
	v_and_b32_e32 v92, 0xffff0000, v66
	v_sub_f32_e32 v61, v61, v92
	v_lshlrev_b32_e32 v92, 16, v66
	v_sub_f32_e32 v60, v60, v92
	v_mul_f32_e32 v61, 0x43800000, v61
	v_mul_f32_e32 v60, 0x43800000, v60
	v_med3_f32 v61, v61, s68, v235
	v_med3_f32 v60, v60, s68, v235
	v_fmac_f32_e32 v95, v63, v168
	v_cvt_pk_fp8_f32 v103, v60, v61
	v_fma_f32 v60, v62, v168, v94
	v_mul_f32_e32 v61, v95, v95
	v_fmac_f32_e32 v61, v60, v60
	v_add_f32_e32 v62, v61, v67
	v_cvt_pk_bf16_f32 v67, v60, v95
	s_nop 0
	v_fma_f32 v57, v57, v168, v89
	v_lshlrev_b32_e32 v61, 16, v67
	v_sub_f32_e32 v60, v60, v61
	v_and_b32_e32 v61, 0xffff0000, v67
	v_sub_f32_e32 v61, v95, v61
	v_mul_f32_e32 v60, 0x43800000, v60
	v_mul_f32_e32 v61, 0x43800000, v61
	v_med3_f32 v60, v60, s68, v235
	v_med3_f32 v61, v61, s68, v235
	v_cvt_pk_fp8_f32 v103, v60, v61 op_sel:[0,0,1]
	v_lshl_add_u64 v[60:61], v[100:101], 1, s[42:43]
	global_store_dwordx4 v[60:61], v[64:67], off
	v_lshl_add_u64 v[60:61], s[44:45], 0, v[100:101]
	global_store_dwordx2 v[60:61], v[102:103], off
	v_fma_f32 v60, v56, v168, v88
	v_mul_f32_e32 v56, v57, v57
	v_fmac_f32_e32 v56, v60, v60
	v_add_f32_e32 v61, v56, v62
	v_cvt_pk_bf16_f32 v56, v60, v57
	v_fmac_f32_e32 v91, v59, v168
	v_and_b32_e32 v62, 0xffff0000, v56
	v_sub_f32_e32 v57, v57, v62
	v_lshlrev_b32_e32 v62, 16, v56
	v_sub_f32_e32 v60, v60, v62
	v_mul_f32_e32 v57, 0x43800000, v57
	v_mul_f32_e32 v60, 0x43800000, v60
	v_med3_f32 v57, v57, s68, v235
	v_med3_f32 v62, v60, s68, v235
	v_mov_b32_e32 v60, v1
	v_cvt_pk_fp8_f32 v60, v62, v57
	v_fma_f32 v58, v58, v168, v90
	v_mul_f32_e32 v57, v91, v91
	v_fmac_f32_e32 v57, v58, v58
	v_add_f32_e32 v59, v57, v61
	v_cvt_pk_bf16_f32 v57, v58, v91
	v_fma_f32 v53, v53, v168, v85
	v_lshlrev_b32_e32 v61, 16, v57
	v_sub_f32_e32 v58, v58, v61
	v_and_b32_e32 v61, 0xffff0000, v57
	v_sub_f32_e32 v61, v91, v61
	v_mul_f32_e32 v58, 0x43800000, v58
	v_mul_f32_e32 v61, 0x43800000, v61
	v_med3_f32 v58, v58, s68, v235
	v_med3_f32 v61, v61, s68, v235
	v_cvt_pk_fp8_f32 v60, v58, v61 op_sel:[0,0,1]
	v_fma_f32 v52, v52, v168, v84
	v_mul_f32_e32 v58, v53, v53
	v_fmac_f32_e32 v58, v52, v52
	v_add_f32_e32 v59, v58, v59
	v_cvt_pk_bf16_f32 v58, v52, v53
	v_fmac_f32_e32 v87, v55, v168
	v_and_b32_e32 v61, 0xffff0000, v58
	v_sub_f32_e32 v53, v53, v61
	v_lshlrev_b32_e32 v61, 16, v58
	v_sub_f32_e32 v52, v52, v61
	v_mul_f32_e32 v53, 0x43800000, v53
	v_mul_f32_e32 v52, 0x43800000, v52
	v_med3_f32 v53, v53, s68, v235
	v_med3_f32 v52, v52, s68, v235
	v_mov_b32_e32 v61, v1
	v_cvt_pk_fp8_f32 v61, v52, v53
	v_fma_f32 v52, v54, v168, v86
	v_mul_f32_e32 v53, v87, v87
	v_fmac_f32_e32 v53, v52, v52
	v_add_f32_e32 v54, v53, v59
	v_cvt_pk_bf16_f32 v59, v52, v87
	v_or_b32_e32 v100, 0x80, v100
	v_lshlrev_b32_e32 v53, 16, v59
	v_sub_f32_e32 v52, v52, v53
	v_and_b32_e32 v53, 0xffff0000, v59
	v_sub_f32_e32 v53, v87, v53
	v_mul_f32_e32 v52, 0x43800000, v52
	v_mul_f32_e32 v53, 0x43800000, v53
	v_med3_f32 v52, v52, s68, v235
	v_med3_f32 v53, v53, s68, v235
	v_cvt_pk_fp8_f32 v61, v52, v53 op_sel:[0,0,1]
	v_lshl_add_u64 v[52:53], v[100:101], 1, s[42:43]
	global_store_dwordx4 v[52:53], v[56:59], off
	v_lshl_add_u64 v[52:53], s[44:45], 0, v[100:101]
	global_store_dwordx2 v[52:53], v[60:61], off
	ds_bpermute_b32 v52, v0, v54
	s_waitcnt lgkmcnt(0)
	v_add_f32_e32 v52, v54, v52
	ds_bpermute_b32 v53, v174, v52
	s_and_saveexec_b64 s[2:3], s[38:39]
	s_cbranch_execz .LBB0_1050
	s_waitcnt lgkmcnt(0)
	v_add_f32_e32 v54, v52, v53
	s_lshl_b32 s20, s56, 2
	v_lshlrev_b64 v[52:53], 7, v[98:99]
	s_ashr_i32 s21, s20, 31
	v_lshl_add_u64 v[52:53], s[8:9], 0, v[52:53]
	v_lshl_add_u64 v[52:53], s[20:21], 2, v[52:53]
	s_lshl_b32 s18, s37, 2
	v_lshl_add_u64 v[52:53], v[52:53], 0, s[18:19]
	global_store_dword v[52:53], v54, off
; __device__ __forceinline__ unsigned cvt_pk_bf16(float lo, float hi) { unsigned r; asm volatile("v_cvt_pk_bf16_f32 %0, %1, %2" : "=v"(r) : "v"(lo), "v"(hi)); return r; }
;     __device__ __forceinline__ void core(const f32x4 (&acc)[2][2][4][2], const Unit& u, int wr, int wc, int fr, int fq, const float (&rsc)[2][4]) const {
;     ...
;             for (int m = 0; m < MB; ++m) { const int row = row0 + ai * HALF + (mh + m) * 16; float sq = 0.f;
;                 const float rs1 = rsc[ai][mh + m];
; #pragma unroll
;                 for (int bj = 0; bj < 2; ++bj) { const size_t idx = (size_t)row * D + col0 + bj * HALF;
;                     unsigned hw[4]; int lw[2] = {0, 0};
; #pragma unroll
;                     for (int pq = 0; pq < 4; ++pq) {
;                         float h0, h1;
;                         if (F32IN) { h0 = (pq < 2) ? xa[m][bj][2 * pq] : xb[m][bj][2 * pq - 4]; h1 = (pq < 2) ? xa[m][bj][2 * pq + 1] : xb[m][bj][2 * pq - 3]; }
;                         else { const unsigned a = va[m][bj][pq]; const int bw = (int)vb[m][bj][pq >> 1]; const hf32x2 lp = (pq & 1) ? __builtin_amdgcn_cvt_pk_f32_fp8(bw, true) : __builtin_amdgcn_cvt_pk_f32_fp8(bw, false);
;                             h0 = __uint_as_float(a << 16) + lp.x * 0.00390625f; h1 = __uint_as_float(a & 0xffff0000u) + lp.y * 0.00390625f; }
;                         const float o0 = h0 + acc[ai][bj][mh + m][pq >> 1][(2 * pq) & 3] * rs1, o1 = h1 + acc[ai][bj][mh + m][pq >> 1][(2 * pq + 1) & 3] * rs1;
;                         sq += o0 * o0 + o1 * o1;
;                         const unsigned hi = cvt_pk_bf16(o0, o1);
;                         hw[pq] = hi;
;                         const float r0 = __builtin_amdgcn_fmed3f((o0 - __uint_as_float(hi << 16)) * 256.0f, -448.0f, 448.0f), r1 = __builtin_amdgcn_fmed3f((o1 - __uint_as_float(hi & 0xffff0000u)) * 256.0f, -448.0f, 448.0f);
;                         lw[pq >> 1] = (pq & 1) ? __builtin_amdgcn_cvt_pk_fp8_f32(r0, r1, lw[pq >> 1], true) : __builtin_amdgcn_cvt_pk_fp8_f32(r0, r1, lw[pq >> 1], false);
;                     }
;                     *(u32x4*)(Hb + idx) = (u32x4){hw[0], hw[1], hw[2], hw[3]}; *(u32x2*)(Hl + idx) = (u32x2){(unsigned)lw[0], (unsigned)lw[1]}; }
;                 sq += __shfl_xor(sq, 16); sq += __shfl_xor(sq, 32); if (fq == 0) ss[(size_t)row * 32 + u.pn * 4 + wc] = sq; }
.LBB0_1050:
	s_or_b64 exec, exec, s[2:3]
	s_nop 0
	v_fma_f32 v54, v48, v169, v80
	v_fma_f32 v49, v49, v169, v81
	v_cvt_pk_bf16_f32 v48, v54, v49
	v_mul_f32_e32 v55, v49, v49
	v_and_b32_e32 v56, 0xffff0000, v48
	v_sub_f32_e32 v49, v49, v56
	v_lshlrev_b32_e32 v56, 16, v48
	v_fmac_f32_e32 v55, v54, v54
	v_sub_f32_e32 v54, v54, v56
	v_mul_f32_e32 v49, 0x43800000, v49
	v_mul_f32_e32 v54, 0x43800000, v54
	v_med3_f32 v49, v49, s68, v235
	v_med3_f32 v56, v54, s68, v235
	v_mov_b32_e32 v54, v1
	v_fmac_f32_e32 v83, v51, v169
	v_cvt_pk_fp8_f32 v54, v56, v49
	v_fma_f32 v50, v50, v169, v82
	v_mul_f32_e32 v49, v83, v83
	v_fmac_f32_e32 v49, v50, v50
	v_add_f32_e32 v51, v55, v49
	v_cvt_pk_bf16_f32 v49, v50, v83
	v_fma_f32 v45, v45, v169, v77
	v_lshlrev_b32_e32 v55, 16, v49
	v_sub_f32_e32 v50, v50, v55
	v_and_b32_e32 v55, 0xffff0000, v49
	v_sub_f32_e32 v55, v83, v55
	v_mul_f32_e32 v50, 0x43800000, v50
	v_mul_f32_e32 v55, 0x43800000, v55
	v_med3_f32 v50, v50, s68, v235
	v_med3_f32 v55, v55, s68, v235
	v_cvt_pk_fp8_f32 v54, v50, v55 op_sel:[0,0,1]
	v_fma_f32 v44, v44, v169, v76
	v_mul_f32_e32 v50, v45, v45
	v_fmac_f32_e32 v50, v44, v44
	v_add_f32_e32 v51, v51, v50
	v_cvt_pk_bf16_f32 v50, v44, v45
	v_fmac_f32_e32 v79, v47, v169
	v_and_b32_e32 v55, 0xffff0000, v50
	v_sub_f32_e32 v45, v45, v55
	v_lshlrev_b32_e32 v55, 16, v50
	v_sub_f32_e32 v44, v44, v55
	v_mul_f32_e32 v45, 0x43800000, v45
	v_mul_f32_e32 v44, 0x43800000, v44
	v_med3_f32 v45, v45, s68, v235
	v_med3_f32 v44, v44, s68, v235
	v_mov_b32_e32 v55, v1
	v_cvt_pk_fp8_f32 v55, v44, v45
	v_fma_f32 v44, v46, v169, v78
	v_mul_f32_e32 v45, v79, v79
	v_fmac_f32_e32 v45, v44, v44
	v_add_f32_e32 v46, v45, v51
	v_cvt_pk_bf16_f32 v51, v44, v79
	s_waitcnt lgkmcnt(0)
	v_lshlrev_b64 v[52:53], 11, v[96:97]
	v_lshlrev_b32_e32 v45, 16, v51
	v_sub_f32_e32 v44, v44, v45
	v_and_b32_e32 v45, 0xffff0000, v51
	v_sub_f32_e32 v45, v79, v45
	v_mul_f32_e32 v44, 0x43800000, v44
	v_mul_f32_e32 v45, 0x43800000, v45
	v_med3_f32 v44, v44, s68, v235
	v_med3_f32 v45, v45, s68, v235
	v_cvt_pk_fp8_f32 v55, v44, v45 op_sel:[0,0,1]
	v_lshl_add_u64 v[52:53], v[52:53], 0, v[162:163]
	v_lshl_add_u64 v[44:45], v[52:53], 1, s[42:43]
	global_store_dwordx4 v[44:45], v[48:51], off
	v_lshl_add_u64 v[44:45], s[44:45], 0, v[52:53]
	s_nop 0
	v_fma_f32 v41, v41, v169, v73
	global_store_dwordx2 v[44:45], v[54:55], off
	v_fma_f32 v44, v40, v169, v72
	v_mul_f32_e32 v40, v41, v41
	v_fmac_f32_e32 v40, v44, v44
	v_add_f32_e32 v45, v40, v46
	v_cvt_pk_bf16_f32 v40, v44, v41
	v_fmac_f32_e32 v75, v43, v169
	v_and_b32_e32 v46, 0xffff0000, v40
	v_sub_f32_e32 v41, v41, v46
	v_lshlrev_b32_e32 v46, 16, v40
	v_sub_f32_e32 v44, v44, v46
	v_mul_f32_e32 v41, 0x43800000, v41
	v_mul_f32_e32 v44, 0x43800000, v44
	v_med3_f32 v41, v41, s68, v235
	v_med3_f32 v46, v44, s68, v235
	v_mov_b32_e32 v44, v1
	v_cvt_pk_fp8_f32 v44, v46, v41
	v_fma_f32 v42, v42, v169, v74
	v_mul_f32_e32 v41, v75, v75
	v_fmac_f32_e32 v41, v42, v42
	v_add_f32_e32 v43, v41, v45
	v_cvt_pk_bf16_f32 v41, v42, v75
	v_fma_f32 v37, v37, v169, v69
	v_lshlrev_b32_e32 v45, 16, v41
	v_sub_f32_e32 v42, v42, v45
	v_and_b32_e32 v45, 0xffff0000, v41
	v_sub_f32_e32 v45, v75, v45
	v_mul_f32_e32 v42, 0x43800000, v42
	v_mul_f32_e32 v45, 0x43800000, v45
	v_med3_f32 v42, v42, s68, v235
	v_med3_f32 v45, v45, s68, v235
	v_cvt_pk_fp8_f32 v44, v42, v45 op_sel:[0,0,1]
	v_fma_f32 v36, v36, v169, v68
	v_mul_f32_e32 v42, v37, v37
	v_fmac_f32_e32 v42, v36, v36
	v_add_f32_e32 v43, v42, v43
	v_cvt_pk_bf16_f32 v42, v36, v37
	v_fmac_f32_e32 v71, v39, v169
	v_and_b32_e32 v45, 0xffff0000, v42
	v_sub_f32_e32 v37, v37, v45
	v_lshlrev_b32_e32 v45, 16, v42
	v_sub_f32_e32 v36, v36, v45
	v_mul_f32_e32 v37, 0x43800000, v37
	v_mul_f32_e32 v36, 0x43800000, v36
	v_med3_f32 v37, v37, s68, v235
	v_med3_f32 v36, v36, s68, v235
	v_mov_b32_e32 v45, v1
	v_cvt_pk_fp8_f32 v45, v36, v37
	v_fma_f32 v36, v38, v169, v70
	v_mul_f32_e32 v37, v71, v71
	v_fmac_f32_e32 v37, v36, v36
	v_add_f32_e32 v37, v37, v43
	v_cvt_pk_bf16_f32 v43, v36, v71
	ds_bpermute_b32 v39, v0, v37
	v_lshlrev_b32_e32 v38, 16, v43
	v_sub_f32_e32 v36, v36, v38
	v_and_b32_e32 v38, 0xffff0000, v43
	v_sub_f32_e32 v38, v71, v38
	v_mul_f32_e32 v36, 0x43800000, v36
	v_mul_f32_e32 v38, 0x43800000, v38
	v_med3_f32 v36, v36, s68, v235
	v_med3_f32 v38, v38, s68, v235
	v_cvt_pk_fp8_f32 v45, v36, v38 op_sel:[0,0,1]
	s_waitcnt lgkmcnt(0)
	v_add_f32_e32 v36, v37, v39
	ds_bpermute_b32 v37, v174, v36
	v_or_b32_e32 v52, 0x80, v52
	v_lshl_add_u64 v[38:39], v[52:53], 1, s[42:43]
	global_store_dwordx4 v[38:39], v[40:43], off
	v_lshl_add_u64 v[38:39], s[44:45], 0, v[52:53]
	global_store_dwordx2 v[38:39], v[44:45], off
	s_and_saveexec_b64 s[2:3], s[38:39]
	s_cbranch_execz .LBB0_1052
	s_waitcnt lgkmcnt(0)
	v_add_f32_e32 v38, v36, v37
	s_lshl_b32 s20, s56, 2
	v_lshlrev_b64 v[36:37], 7, v[96:97]
	s_ashr_i32 s21, s20, 31
	v_lshl_add_u64 v[36:37], s[8:9], 0, v[36:37]
	v_lshl_add_u64 v[36:37], s[20:21], 2, v[36:37]
	s_lshl_b32 s18, s37, 2
	v_lshl_add_u64 v[36:37], v[36:37], 0, s[18:19]
	global_store_dword v[36:37], v38, off
;     __device__ __forceinline__ void core(const f32x4 (&acc)[2][2][4][2], const Unit& u, int wr, int wc, int fr, int fq, const float (&rsc)[2][4]) const {
;     ...
; #pragma unroll
;             for (int m = 0; m < MB; ++m)
; #pragma unroll
;                 for (int bj = 0; bj < 2; ++bj) { const size_t idx = (size_t)(row0 + ai * HALF + (mh + m) * 16) * D + col0 + bj * HALF;
;                     if (F32IN) { xa[m][bj] = *(const f32x4*)(Xin + idx); xb[m][bj] = *(const f32x4*)(Xin + idx + 4); }
;                     else { va[m][bj] = *(const u32x4*)(Hb + idx); vb[m][bj] = *(const u32x2*)(Hl + idx); } }
; #pragma unroll
;             for (int m = 0; m < MB; ++m) { const int row = row0 + ai * HALF + (mh + m) * 16; float sq = 0.f;
;                 const float rs1 = rsc[ai][mh + m];
; #pragma unroll
;                 for (int bj = 0; bj < 2; ++bj) { const size_t idx = (size_t)row * D + col0 + bj * HALF;
;                     unsigned hw[4]; int lw[2] = {0, 0};
; #pragma unroll
;                     for (int pq = 0; pq < 4; ++pq) {
;                         float h0, h1;
;                         if (F32IN) { h0 = (pq < 2) ? xa[m][bj][2 * pq] : xb[m][bj][2 * pq - 4]; h1 = (pq < 2) ? xa[m][bj][2 * pq + 1] : xb[m][bj][2 * pq - 3]; }
;                         else { const unsigned a = va[m][bj][pq]; const int bw = (int)vb[m][bj][pq >> 1]; const hf32x2 lp = (pq & 1) ? __builtin_amdgcn_cvt_pk_f32_fp8(bw, true) : __builtin_amdgcn_cvt_pk_f32_fp8(bw, false);
;                             h0 = __uint_as_float(a << 16) + lp.x * 0.00390625f; h1 = __uint_as_float(a & 0xffff0000u) + lp.y * 0.00390625f; }
;                         const float o0 = h0 + acc[ai][bj][mh + m][pq >> 1][(2 * pq) & 3] * rs1, o1 = h1 + acc[ai][bj][mh + m][pq >> 1][(2 * pq + 1) & 3] * rs1;
;                         sq += o0 * o0 + o1 * o1;
;                         const unsigned hi = cvt_pk_bf16(o0, o1);
;                         hw[pq] = hi;
;                         const float r0 = __builtin_amdgcn_fmed3f((o0 - __uint_as_float(hi << 16)) * 256.0f, -448.0f, 448.0f), r1 = __builtin_amdgcn_fmed3f((o1 - __uint_as_float(hi & 0xffff0000u)) * 256.0f, -448.0f, 448.0f);
;                         lw[pq >> 1] = (pq & 1) ? __builtin_amdgcn_cvt_pk_fp8_f32(r0, r1, lw[pq >> 1], true) : __builtin_amdgcn_cvt_pk_fp8_f32(r0, r1, lw[pq >> 1], false);
;                     }
.LBB0_1052:
	s_or_b64 exec, exec, s[2:3]
	v_add_u32_e32 v66, 0xa0, v164
	v_ashrrev_i32_e32 v67, 31, v66
	s_waitcnt lgkmcnt(0)
	v_add_u32_e32 v64, 0xb0, v164
	v_ashrrev_i32_e32 v65, 31, v64
	s_waitcnt vmcnt(8)
	v_mov_b32_e32 v60, v214
	v_mov_b32_e32 v61, v215
	v_mov_b32_e32 v62, v216
	v_mov_b32_e32 v63, v217
	v_mov_b32_e32 v70, v218
	v_mov_b32_e32 v71, v219
	v_mov_b32_e32 v72, v220
	v_mov_b32_e32 v73, v221
	v_mov_b32_e32 v52, v236
	v_mov_b32_e32 v53, v237
	v_mov_b32_e32 v54, v238
	v_mov_b32_e32 v55, v239
	v_mov_b32_e32 v56, v240
	v_mov_b32_e32 v57, v241
	v_mov_b32_e32 v58, v242
	v_mov_b32_e32 v59, v243
	v_mov_b32_e32 v44, v244
	v_mov_b32_e32 v45, v245
	v_mov_b32_e32 v46, v246
	v_mov_b32_e32 v47, v247
	v_mov_b32_e32 v48, v248
	v_mov_b32_e32 v49, v249
	v_mov_b32_e32 v50, v250
	v_mov_b32_e32 v51, v251
	v_mov_b32_e32 v36, v148
	v_mov_b32_e32 v37, v149
	v_mov_b32_e32 v38, v150
	v_mov_b32_e32 v39, v151
	v_mov_b32_e32 v40, v152
	v_mov_b32_e32 v41, v153
	v_mov_b32_e32 v42, v154
	v_mov_b32_e32 v43, v155
	v_lshlrev_b64 v[68:69], 11, v[66:67]
	v_lshl_add_u64 v[68:69], v[68:69], 0, v[162:163]
	s_nop 0
	v_fma_f32 v29, v29, v2, v61
	s_nop 0
	v_fma_f32 v70, v32, v2, v70
	v_fma_f32 v33, v33, v2, v71
	v_cvt_pk_bf16_f32 v32, v70, v33
	v_mul_f32_e32 v71, v33, v33
	v_and_b32_e32 v74, 0xffff0000, v32
	v_sub_f32_e32 v33, v33, v74
	v_lshlrev_b32_e32 v74, 16, v32
	v_fmac_f32_e32 v71, v70, v70
	v_sub_f32_e32 v70, v70, v74
	v_mul_f32_e32 v33, 0x43800000, v33
	v_mul_f32_e32 v70, 0x43800000, v70
	v_med3_f32 v33, v33, s68, v235
	v_med3_f32 v74, v70, s68, v235
	v_mov_b32_e32 v70, v1
	v_fmac_f32_e32 v73, v35, v2
	v_cvt_pk_fp8_f32 v70, v74, v33
	v_fma_f32 v34, v34, v2, v72
	v_mul_f32_e32 v33, v73, v73
	v_fmac_f32_e32 v33, v34, v34
	v_add_f32_e32 v35, v71, v33
	v_cvt_pk_bf16_f32 v33, v34, v73
	v_fma_f32 v28, v28, v2, v60
	v_lshlrev_b32_e32 v71, 16, v33
	v_sub_f32_e32 v34, v34, v71
	v_and_b32_e32 v71, 0xffff0000, v33
	v_sub_f32_e32 v71, v73, v71
	v_mul_f32_e32 v34, 0x43800000, v34
	v_mul_f32_e32 v71, 0x43800000, v71
	v_med3_f32 v34, v34, s68, v235
	v_med3_f32 v71, v71, s68, v235
	v_cvt_pk_fp8_f32 v70, v34, v71 op_sel:[0,0,1]
	v_mul_f32_e32 v34, v29, v29
	v_fmac_f32_e32 v34, v28, v28
	v_add_f32_e32 v35, v35, v34
	v_cvt_pk_bf16_f32 v34, v28, v29
	v_mov_b32_e32 v71, v1
	v_and_b32_e32 v60, 0xffff0000, v34
	v_sub_f32_e32 v29, v29, v60
	v_lshlrev_b32_e32 v60, 16, v34
	v_sub_f32_e32 v28, v28, v60
	v_mul_f32_e32 v29, 0x43800000, v29
	v_mul_f32_e32 v28, 0x43800000, v28
	v_med3_f32 v29, v29, s68, v235
	v_med3_f32 v28, v28, s68, v235
	v_fmac_f32_e32 v63, v31, v2
	v_cvt_pk_fp8_f32 v71, v28, v29
	v_fma_f32 v28, v30, v2, v62
	v_mul_f32_e32 v29, v63, v63
	v_fmac_f32_e32 v29, v28, v28
	v_add_f32_e32 v30, v29, v35
	v_cvt_pk_bf16_f32 v35, v28, v63
	s_nop 0
	v_fma_f32 v25, v25, v2, v57
	v_lshlrev_b32_e32 v29, 16, v35
	v_sub_f32_e32 v28, v28, v29
	v_and_b32_e32 v29, 0xffff0000, v35
	v_sub_f32_e32 v29, v63, v29
	v_mul_f32_e32 v28, 0x43800000, v28
	v_mul_f32_e32 v29, 0x43800000, v29
	v_med3_f32 v28, v28, s68, v235
	v_med3_f32 v29, v29, s68, v235
	v_cvt_pk_fp8_f32 v71, v28, v29 op_sel:[0,0,1]
	v_lshl_add_u64 v[28:29], v[68:69], 1, s[42:43]
	global_store_dwordx4 v[28:29], v[32:35], off
	v_lshl_add_u64 v[28:29], s[44:45], 0, v[68:69]
	global_store_dwordx2 v[28:29], v[70:71], off
	v_fma_f32 v28, v24, v2, v56
	v_mul_f32_e32 v24, v25, v25
	v_fmac_f32_e32 v24, v28, v28
	v_add_f32_e32 v29, v24, v30
	v_cvt_pk_bf16_f32 v24, v28, v25
	v_fmac_f32_e32 v59, v27, v2
	v_and_b32_e32 v30, 0xffff0000, v24
	v_sub_f32_e32 v25, v25, v30
	v_lshlrev_b32_e32 v30, 16, v24
	v_sub_f32_e32 v28, v28, v30
	v_mul_f32_e32 v25, 0x43800000, v25
	v_mul_f32_e32 v28, 0x43800000, v28
	v_med3_f32 v25, v25, s68, v235
	v_med3_f32 v30, v28, s68, v235
	v_mov_b32_e32 v28, v1
	v_cvt_pk_fp8_f32 v28, v30, v25
	v_fma_f32 v26, v26, v2, v58
	v_mul_f32_e32 v25, v59, v59
	v_fmac_f32_e32 v25, v26, v26
	v_add_f32_e32 v27, v25, v29
	v_cvt_pk_bf16_f32 v25, v26, v59
	v_fma_f32 v21, v21, v2, v53
	v_lshlrev_b32_e32 v29, 16, v25
	v_sub_f32_e32 v26, v26, v29
	v_and_b32_e32 v29, 0xffff0000, v25
	v_sub_f32_e32 v29, v59, v29
	v_mul_f32_e32 v26, 0x43800000, v26
	v_mul_f32_e32 v29, 0x43800000, v29
	v_med3_f32 v26, v26, s68, v235
	v_med3_f32 v29, v29, s68, v235
	v_cvt_pk_fp8_f32 v28, v26, v29 op_sel:[0,0,1]
	v_fma_f32 v20, v20, v2, v52
	v_mul_f32_e32 v26, v21, v21
	v_fmac_f32_e32 v26, v20, v20
	v_add_f32_e32 v27, v26, v27
	v_cvt_pk_bf16_f32 v26, v20, v21
	v_fmac_f32_e32 v55, v23, v2
	v_and_b32_e32 v29, 0xffff0000, v26
	v_sub_f32_e32 v21, v21, v29
	v_lshlrev_b32_e32 v29, 16, v26
	v_sub_f32_e32 v20, v20, v29
	v_mul_f32_e32 v21, 0x43800000, v21
	v_mul_f32_e32 v20, 0x43800000, v20
	v_med3_f32 v21, v21, s68, v235
	v_med3_f32 v20, v20, s68, v235
	v_mov_b32_e32 v29, v1
	v_cvt_pk_fp8_f32 v29, v20, v21
	v_fma_f32 v20, v22, v2, v54
	v_mul_f32_e32 v2, v55, v55
	v_fmac_f32_e32 v2, v20, v20
	v_add_f32_e32 v2, v2, v27
	v_cvt_pk_bf16_f32 v27, v20, v55
	v_or_b32_e32 v68, 0x80, v68
	v_lshlrev_b32_e32 v21, 16, v27
	v_sub_f32_e32 v20, v20, v21
	v_and_b32_e32 v21, 0xffff0000, v27
	v_sub_f32_e32 v21, v55, v21
	v_mul_f32_e32 v20, 0x43800000, v20
	v_mul_f32_e32 v21, 0x43800000, v21
	v_med3_f32 v20, v20, s68, v235
	v_med3_f32 v21, v21, s68, v235
	v_cvt_pk_fp8_f32 v29, v20, v21 op_sel:[0,0,1]
	v_lshl_add_u64 v[20:21], v[68:69], 1, s[42:43]
	global_store_dwordx4 v[20:21], v[24:27], off
	v_lshl_add_u64 v[20:21], s[44:45], 0, v[68:69]
	global_store_dwordx2 v[20:21], v[28:29], off
	ds_bpermute_b32 v20, v0, v2
	s_waitcnt lgkmcnt(0)
	v_add_f32_e32 v2, v2, v20
	ds_bpermute_b32 v20, v174, v2
	s_and_saveexec_b64 s[2:3], s[38:39]
	s_cbranch_execz .LBB0_1054
	s_waitcnt lgkmcnt(0)
	v_add_f32_e32 v2, v2, v20
	s_lshl_b32 s20, s56, 2
	v_lshlrev_b64 v[20:21], 7, v[66:67]
	s_ashr_i32 s21, s20, 31
	v_lshl_add_u64 v[20:21], s[8:9], 0, v[20:21]
	v_lshl_add_u64 v[20:21], s[20:21], 2, v[20:21]
	s_lshl_b32 s18, s37, 2
	v_lshl_add_u64 v[20:21], v[20:21], 0, s[18:19]
	global_store_dword v[20:21], v2, off
; __device__ __forceinline__ unsigned cvt_pk_bf16(float lo, float hi) { unsigned r; asm volatile("v_cvt_pk_bf16_f32 %0, %1, %2" : "=v"(r) : "v"(lo), "v"(hi)); return r; }
;     __device__ __forceinline__ void core(const f32x4 (&acc)[2][2][4][2], const Unit& u, int wr, int wc, int fr, int fq, const float (&rsc)[2][4]) const {
;     ...
;             for (int m = 0; m < MB; ++m) { const int row = row0 + ai * HALF + (mh + m) * 16; float sq = 0.f;
;                 const float rs1 = rsc[ai][mh + m];
; #pragma unroll
;                 for (int bj = 0; bj < 2; ++bj) { const size_t idx = (size_t)row * D + col0 + bj * HALF;
;                     unsigned hw[4]; int lw[2] = {0, 0};
; #pragma unroll
;                     for (int pq = 0; pq < 4; ++pq) {
;                         float h0, h1;
;                         if (F32IN) { h0 = (pq < 2) ? xa[m][bj][2 * pq] : xb[m][bj][2 * pq - 4]; h1 = (pq < 2) ? xa[m][bj][2 * pq + 1] : xb[m][bj][2 * pq - 3]; }
;                         else { const unsigned a = va[m][bj][pq]; const int bw = (int)vb[m][bj][pq >> 1]; const hf32x2 lp = (pq & 1) ? __builtin_amdgcn_cvt_pk_f32_fp8(bw, true) : __builtin_amdgcn_cvt_pk_f32_fp8(bw, false);
;                             h0 = __uint_as_float(a << 16) + lp.x * 0.00390625f; h1 = __uint_as_float(a & 0xffff0000u) + lp.y * 0.00390625f; }
;                         const float o0 = h0 + acc[ai][bj][mh + m][pq >> 1][(2 * pq) & 3] * rs1, o1 = h1 + acc[ai][bj][mh + m][pq >> 1][(2 * pq + 1) & 3] * rs1;
;                         sq += o0 * o0 + o1 * o1;
;                         const unsigned hi = cvt_pk_bf16(o0, o1);
;                         hw[pq] = hi;
;                         const float r0 = __builtin_amdgcn_fmed3f((o0 - __uint_as_float(hi << 16)) * 256.0f, -448.0f, 448.0f), r1 = __builtin_amdgcn_fmed3f((o1 - __uint_as_float(hi & 0xffff0000u)) * 256.0f, -448.0f, 448.0f);
;                         lw[pq >> 1] = (pq & 1) ? __builtin_amdgcn_cvt_pk_fp8_f32(r0, r1, lw[pq >> 1], true) : __builtin_amdgcn_cvt_pk_fp8_f32(r0, r1, lw[pq >> 1], false);
;                     }
;                     *(u32x4*)(Hb + idx) = (u32x4){hw[0], hw[1], hw[2], hw[3]}; *(u32x2*)(Hl + idx) = (u32x2){(unsigned)lw[0], (unsigned)lw[1]}; }
;                 sq += __shfl_xor(sq, 16); sq += __shfl_xor(sq, 32); if (fq == 0) ss[(size_t)row * 32 + u.pn * 4 + wc] = sq; }
.LBB0_1054:
	s_or_b64 exec, exec, s[2:3]
	s_nop 0
	v_fma_f32 v2, v16, v3, v48
	v_fma_f32 v17, v17, v3, v49
	v_cvt_pk_bf16_f32 v16, v2, v17
	v_mul_f32_e32 v23, v17, v17
	v_and_b32_e32 v22, 0xffff0000, v16
	v_sub_f32_e32 v17, v17, v22
	v_lshlrev_b32_e32 v22, 16, v16
	v_fmac_f32_e32 v23, v2, v2
	v_sub_f32_e32 v2, v2, v22
	v_mul_f32_e32 v17, 0x43800000, v17
	v_mul_f32_e32 v2, 0x43800000, v2
	v_med3_f32 v17, v17, s68, v235
	v_med3_f32 v2, v2, s68, v235
	v_mov_b32_e32 v22, v1
	v_fmac_f32_e32 v51, v19, v3
	v_cvt_pk_fp8_f32 v22, v2, v17
	v_fma_f32 v2, v18, v3, v50
	v_mul_f32_e32 v17, v51, v51
	v_fmac_f32_e32 v17, v2, v2
	v_add_f32_e32 v18, v23, v17
	v_cvt_pk_bf16_f32 v17, v2, v51
	v_mov_b32_e32 v23, v1
	v_lshlrev_b32_e32 v19, 16, v17
	v_sub_f32_e32 v2, v2, v19
	v_and_b32_e32 v19, 0xffff0000, v17
	v_sub_f32_e32 v19, v51, v19
	v_mul_f32_e32 v2, 0x43800000, v2
	v_mul_f32_e32 v19, 0x43800000, v19
	v_med3_f32 v2, v2, s68, v235
	v_med3_f32 v19, v19, s68, v235
	v_cvt_pk_fp8_f32 v22, v2, v19 op_sel:[0,0,1]
	v_fma_f32 v2, v12, v3, v44
	v_fma_f32 v12, v13, v3, v45
	v_mul_f32_e32 v13, v12, v12
	v_fmac_f32_e32 v13, v2, v2
	v_add_f32_e32 v13, v18, v13
	v_cvt_pk_bf16_f32 v18, v2, v12
	v_fmac_f32_e32 v47, v15, v3
	v_and_b32_e32 v19, 0xffff0000, v18
	v_sub_f32_e32 v12, v12, v19
	v_lshlrev_b32_e32 v19, 16, v18
	v_sub_f32_e32 v2, v2, v19
	v_mul_f32_e32 v12, 0x43800000, v12
	v_mul_f32_e32 v2, 0x43800000, v2
	v_med3_f32 v12, v12, s68, v235
	v_med3_f32 v2, v2, s68, v235
	v_cvt_pk_fp8_f32 v23, v2, v12
	v_fma_f32 v2, v14, v3, v46
	v_mul_f32_e32 v12, v47, v47
	v_fmac_f32_e32 v12, v2, v2
	v_add_f32_e32 v14, v12, v13
	v_cvt_pk_bf16_f32 v19, v2, v47
	s_waitcnt lgkmcnt(0)
	v_lshlrev_b64 v[20:21], 11, v[64:65]
	v_lshlrev_b32_e32 v12, 16, v19
	v_sub_f32_e32 v2, v2, v12
	v_and_b32_e32 v12, 0xffff0000, v19
	v_sub_f32_e32 v12, v47, v12
	v_mul_f32_e32 v2, 0x43800000, v2
	v_mul_f32_e32 v12, 0x43800000, v12
	v_med3_f32 v2, v2, s68, v235
	v_med3_f32 v12, v12, s68, v235
	v_cvt_pk_fp8_f32 v23, v2, v12 op_sel:[0,0,1]
	v_lshl_add_u64 v[20:21], v[20:21], 0, v[162:163]
	s_nop 0
	v_fma_f32 v9, v9, v3, v41
	v_lshl_add_u64 v[12:13], v[20:21], 1, s[42:43]
	v_fma_f32 v2, v8, v3, v40
	v_mul_f32_e32 v8, v9, v9
	global_store_dwordx4 v[12:13], v[16:19], off
	v_lshl_add_u64 v[12:13], s[44:45], 0, v[20:21]
	v_fmac_f32_e32 v8, v2, v2
	global_store_dwordx2 v[12:13], v[22:23], off
	v_add_f32_e32 v13, v8, v14
	v_cvt_pk_bf16_f32 v8, v2, v9
	v_fmac_f32_e32 v43, v11, v3
	v_and_b32_e32 v12, 0xffff0000, v8
	v_sub_f32_e32 v9, v9, v12
	v_lshlrev_b32_e32 v12, 16, v8
	v_sub_f32_e32 v2, v2, v12
	v_mul_f32_e32 v9, 0x43800000, v9
	v_mul_f32_e32 v2, 0x43800000, v2
	v_med3_f32 v9, v9, s68, v235
	v_med3_f32 v2, v2, s68, v235
	v_mov_b32_e32 v12, v1
	v_cvt_pk_fp8_f32 v12, v2, v9
	v_fma_f32 v2, v10, v3, v42
	v_mul_f32_e32 v9, v43, v43
	v_fmac_f32_e32 v9, v2, v2
	v_add_f32_e32 v10, v9, v13
	v_cvt_pk_bf16_f32 v9, v2, v43
	v_mov_b32_e32 v13, v1
	v_lshlrev_b32_e32 v11, 16, v9
	v_sub_f32_e32 v2, v2, v11
	v_and_b32_e32 v11, 0xffff0000, v9
	v_sub_f32_e32 v11, v43, v11
	v_mul_f32_e32 v2, 0x43800000, v2
	v_mul_f32_e32 v11, 0x43800000, v11
	v_med3_f32 v2, v2, s68, v235
	v_med3_f32 v11, v11, s68, v235
	v_cvt_pk_fp8_f32 v12, v2, v11 op_sel:[0,0,1]
	v_fma_f32 v2, v4, v3, v36
	v_fma_f32 v4, v5, v3, v37
	v_mul_f32_e32 v5, v4, v4
	v_fmac_f32_e32 v5, v2, v2
	v_add_f32_e32 v5, v5, v10
	v_cvt_pk_bf16_f32 v10, v2, v4
	v_fmac_f32_e32 v39, v7, v3
	v_and_b32_e32 v11, 0xffff0000, v10
	v_sub_f32_e32 v4, v4, v11
	v_lshlrev_b32_e32 v11, 16, v10
	v_sub_f32_e32 v2, v2, v11
	v_mul_f32_e32 v4, 0x43800000, v4
	v_mul_f32_e32 v2, 0x43800000, v2
	v_med3_f32 v4, v4, s68, v235
	v_med3_f32 v2, v2, s68, v235
	v_cvt_pk_fp8_f32 v13, v2, v4
	v_fma_f32 v2, v6, v3, v38
	v_mul_f32_e32 v3, v39, v39
	v_fmac_f32_e32 v3, v2, v2
	v_add_f32_e32 v3, v3, v5
	ds_bpermute_b32 v0, v0, v3
	v_cvt_pk_bf16_f32 v11, v2, v39
	v_or_b32_e32 v20, 0x80, v20
	v_lshlrev_b32_e32 v4, 16, v11
	v_sub_f32_e32 v2, v2, v4
	v_and_b32_e32 v4, 0xffff0000, v11
	v_sub_f32_e32 v4, v39, v4
	v_mul_f32_e32 v2, 0x43800000, v2
	v_mul_f32_e32 v4, 0x43800000, v4
	v_med3_f32 v2, v2, s68, v235
	v_med3_f32 v4, v4, s68, v235
	s_waitcnt lgkmcnt(0)
	v_add_f32_e32 v0, v3, v0
	v_cvt_pk_fp8_f32 v13, v2, v4 op_sel:[0,0,1]
	ds_bpermute_b32 v2, v174, v0
	v_lshl_add_u64 v[4:5], v[20:21], 1, s[42:43]
	global_store_dwordx4 v[4:5], v[8:11], off
	v_lshl_add_u64 v[4:5], s[44:45], 0, v[20:21]
	global_store_dwordx2 v[4:5], v[12:13], off
	s_and_saveexec_b64 s[2:3], s[38:39]
	s_cbranch_execz .LBB0_1056
	s_waitcnt lgkmcnt(0)
	v_add_f32_e32 v0, v0, v2
	s_lshl_b32 s20, s56, 2
	v_lshlrev_b64 v[2:3], 7, v[64:65]
	s_ashr_i32 s21, s20, 31
	v_lshl_add_u64 v[2:3], s[8:9], 0, v[2:3]
	v_lshl_add_u64 v[2:3], s[20:21], 2, v[2:3]
	s_lshl_b32 s18, s37, 2
	v_lshl_add_u64 v[2:3], v[2:3], 0, s[18:19]
	global_store_dword v[2:3], v0, off
